# pool phase: s_setprio 1 for the heavy-window waves (W=8/16) of each SIMD pair, reset at phase end
# speedup vs baseline: 1.0037x; 1.0037x over previous
.LBB0_302:
	s_setprio 1
	v_cmp_eq_u32_e32 vcc, 2, v129
	s_mov_b64 s[52:53], -1
	s_and_saveexec_b64 s[50:51], vcc
	s_cbranch_execz .LBB0_318
	v_cmp_lt_u32_e32 vcc, 6, v130
	v_mov_b32_e32 v12, 0
	v_mov_b32_e32 v16, 0
	v_mov_b32_e32 v17, 0
	v_mov_b32_e32 v18, 0
	v_mov_b32_e32 v19, 0
	s_and_saveexec_b64 s[52:53], vcc
	s_cbranch_execz .LBB0_305
	v_add_u32_e32 v14, -10, v106
	v_ashrrev_i32_e32 v15, 31, v14
	v_lshlrev_b64 v[14:15], 12, v[14:15]
	v_lshl_add_u64 v[14:15], v[0:1], 0, v[14:15]
	global_load_dwordx4 v[16:19], v[14:15], off

.LBB0_320:
	s_setprio 1
	v_cmp_lt_u32_e32 vcc, 14, v130
	v_mov_b32_e32 v12, 0
	v_mov_b32_e32 v48, 0
	v_mov_b32_e32 v49, 0
	v_mov_b32_e32 v50, 0
	v_mov_b32_e32 v51, 0
	s_and_saveexec_b64 s[50:51], vcc
	s_cbranch_execz .LBB0_322
	v_subrev_u32_e32 v14, 18, v106
	v_ashrrev_i32_e32 v15, 31, v14
	v_lshlrev_b64 v[14:15], 12, v[14:15]
	v_lshl_add_u64 v[14:15], v[0:1], 0, v[14:15]
	global_load_dwordx4 v[48:51], v[14:15], off

.LBB0_362:
	s_setprio 0
	s_or_b64 exec, exec, s[0:1]
	s_waitcnt vmcnt(0)
	v_readlane_b32 s2, v252, 2
	v_readlane_b32 s3, v252, 3
	s_barrier
	s_and_saveexec_b64 s[0:1], s[2:3]
	s_cbranch_execz .LBB0_414
	v_mov_b32_e32 v0, 0x20000
	ds_read_b64 v[0:1], v0
	s_getreg_b32 s44, hwreg(HW_REG_XCC_ID, 0, 4)
	s_lshl_b32 s44, s44, 7
	s_add_u32 s44, s44, 0xdc03600
	v_mov_b32_e32 v2, s44
	v_mov_b32_e32 v4, 1
	s_waitcnt vmcnt(0) lgkmcnt(0)
	global_atomic_add v5, v2, v4, s[42:43] sc0
	buffer_inv sc1
	s_add_u32 s100, s100, 1
	v_readfirstlane_b32 s46, v0
	v_readfirstlane_b32 s47, v1
	v_mov_b32_e32 v2, 0xdc03e00
	s_nop 3
	s_mul_i32 s48, s46, s100
	s_mul_i32 s49, s47, s100
	s_waitcnt vmcnt(1)
	v_readfirstlane_b32 s50, v5
	s_nop 3
	s_add_u32 s50, s50, 1
	s_cmp_lg_u32 s50, s48
	s_cbranch_scc1 .Lxb3_poll
	buffer_wbl2 sc1
	s_waitcnt vmcnt(0)
	global_atomic_add v2, v4, s[42:43]
